# P1 pass_h_fold run by WGs 128-255 only (2 chunks per wave) overlapping fold items on WGs 0-127; transposes back on WGs 0-95
# baseline (speedup 1.0000x reference)
; __device__ __forceinline__ void p0_prologue(const Params& p, LAS unsigned char* lds) {
;     ...
;     const int gw = blockIdx.x * NWAVES + wave, NGW = G * NWAVES;
;     constexpr int I_QK = 16 * 32, I_V = 16 * 16;
;     for (int it = gw; it < I_QK + I_V; it += NGW) {
;         int r = it;
;         if (r < I_QK) { const int kb = r >> 5, nb = r & 31; p0_transpose_item(p.w_in, 2048, 512 + nb * 32, DM, (bf16_t*)(p.ws + WS_WQK), nb * 32, nullptr, scr, kb, lane); continue; } r -= I_QK;
;         { const int kb = r >> 4, nb = r & 15; p0_transpose_item(p.w_in, 2048, 1536 + nb * 32, DM, (bf16_t*)(p.ws + WS_WA), 1024 + nb * 32, nullptr, scr, kb, lane); }
;     }
.LBB0_76:
	s_xor_b32 s98, s2, 0x80
	s_cmpk_eq_i32 s3, 0x100
	s_mov_b32 s98, s2
	v_lshl_add_u32 v14, s98, 3, v171
	s_movk_i32 s4, 0x300
	v_cmp_gt_i32_e32 vcc, s4, v14
	s_and_saveexec_b64 s[4:5], vcc
	s_cbranch_execz .LBB0_83
	v_lshlrev_b32_e32 v1, 3, v170
	v_lshrrev_b32_e32 v15, 3, v37
	v_and_b32_e32 v1, 56, v1
	v_lshl_add_u32 v0, v171, 14, 0
	v_mul_u32_u24_e32 v2, 0x84, v1
	v_lshlrev_b32_e32 v3, 2, v15
	v_lshl_add_u32 v8, v107, 2, v0
	v_add3_u32 v16, v0, v2, v3
	v_lshlrev_b32_e32 v0, 1, v1
	v_mov_b32_e32 v1, 0
	v_lshl_add_u64 v[2:3], s[8:9], 0, v[0:1]
	v_lshl_add_u64 v[4:5], s[34:35], 0, v[0:1]
	v_lshlrev_b32_e32 v0, 2, v171
	v_mul_u32_u24_e32 v9, 0x84, v106
	v_lshl_add_u32 v20, s98, 5, v0
	v_lshlrev_b32_e32 v0, 1, v171
	s_mov_b64 s[8:9], 0x300000
	v_mov_b32_e32 v37, v1
	v_lshl_add_u32 v21, s98, 4, v0
	v_lshlrev_b32_e32 v0, 5, v171
	v_add_u32_e32 v23, v8, v9
	s_lshl_b32 s10, s3, 3
	v_or_b32_e32 v17, 8, v15
	v_or_b32_e32 v18, 16, v15
	v_or_b32_e32 v19, 24, v15
	v_lshl_add_u64 v[4:5], v[4:5], 0, s[8:9]
	s_waitcnt lgkmcnt(0)
	v_lshl_add_u64 v[6:7], s[46:47], 0, v[36:37]
	s_lshl_b32 s11, s3, 5
	s_lshl_b32 s16, s3, 4
	v_lshl_add_u32 v22, s98, 8, v0
	s_lshl_b32 s17, s3, 8
	s_mov_b64 s[8:9], 0
	s_movk_i32 s18, 0x1ff
	s_mov_b64 s[12:13], 0x1800
	s_movk_i32 s19, 0x2ff
	v_add_u32_e32 v24, 0x400, v23
	v_add_u32_e32 v25, 0x800, v23
	v_add_u32_e32 v26, 0xc00, v23
	v_add_u32_e32 v27, 0x1000, v23
	v_add_u32_e32 v28, 0x1400, v23
	v_add_u32_e32 v29, 0x1800, v23
	v_add_u32_e32 v30, 0x1c00, v23
	s_branch .LBB0_79

; __device__ __forceinline__ void pass_h_fold(const float* src, const float* g, const float* mod, bf16_t* H, bf16_t* HE, bf16_t* HO) {
;     const int vb = (gridDim.x & 7) ? (int)blockIdx.x : (int)((blockIdx.x & 7) * (gridDim.x >> 3) + (blockIdx.x >> 3));
;     const int lane = threadIdx.x & 63, gw = vb * NWAVES + (threadIdx.x >> 6), NGW = gridDim.x * NWAVES;
;     for (int ch = gw; ch < 2048; ch += NGW) {
;         const int b = ch >> 8, sb = (ch & 255) * 4;
;         f32x4 mul[4], sh[4];
; #pragma unroll
;         for (int j = 0; j < 4; ++j) { const f32x4 gg = ((const f32x4*)g)[lane + 64 * j], sc = ((const f32x4*)(mod + (size_t)b * NMOD + DM))[lane + 64 * j];
;             mul[j] = gg * (1.0f + sc); sh[j] = ((const f32x4*)(mod + (size_t)b * NMOD))[lane + 64 * j]; }
; #pragma unroll
;         for (int half = 0; half < 2; ++half) {
;             f32x4 v[2][2][4];
; #pragma unroll
;             for (int q = 0; q < 2; ++q) { const int s = sb + half * 2 + q, pr = (s == 0) ? SEQ / 2 : SEQ - s;
;                 const f32x4* x0 = (const f32x4*)(src + (size_t)(b * SEQ + s) * DM) + lane; const f32x4* x1 = (const f32x4*)(src + (size_t)(b * SEQ + pr) * DM) + lane;
; #pragma unroll
;                 for (int j = 0; j < 4; ++j) { v[q][0][j] = x0[64 * j]; v[q][1][j] = x1[64 * j]; } }
; #pragma unroll
;             for (int q = 0; q < 2; ++q) { const int s = sb + half * 2 + q, pr = (s == 0) ? SEQ / 2 : SEQ - s;
;                 float t0 = 0.f, t1 = 0.f;
; #pragma unroll
;                 for (int j = 0; j < 4; ++j) { const f32x4 a = v[q][0][j], c = v[q][1][j]; t0 += (a[0] * a[0] + a[1] * a[1]) + (a[2] * a[2] + a[3] * a[3]); t1 += (c[0] * c[0] + c[1] * c[1]) + (c[2] * c[2] + c[3] * c[3]); }
;                 t0 = wave_sum(t0); t1 = wave_sum(t1);
;                 const float r0 = 1.0f / sqrtf(t0 * (1.0f / DM) + EPS), r1 = 1.0f / sqrtf(t1 * (1.0f / DM) + EPS);
.LBB0_96:
	s_cmp_lt_i32 s96, 2
	s_cselect_b64 s[6:7], -1, 0
	s_waitcnt lgkmcnt(0)
	s_and_b64 s[38:39], s[6:7], s[4:5]
	s_andn2_b64 vcc, exec, s[38:39]
	s_lshr_b32 s48, s3, 3
	s_cbranch_vccnz .LBB0_101
	s_and_b32 s5, s2, 7
	s_mul_i32 s5, s48, s5
	s_lshr_b32 s6, s2, 3
	s_and_b32 s4, s3, 7
	s_add_i32 s5, s5, s6
	s_cmp_eq_u32 s4, 0
	s_cselect_b32 s4, s5, s2
	s_lshl_b32 s26, s3, 3
	s_lshl_b32 s27, s3, 5
	s_movk_i32 s41, 0x7ff
	s_cmpk_lg_i32 s3, 0x100
	s_cbranch_scc1 .Lp1_generic
	s_cmpk_lt_u32 s2, 0x80
	s_cbranch_scc1 .LBB0_101
	s_add_i32 s4, s4, -16
	s_lshl_b32 s41, s4, 3
	s_addk_i32 s41, 0x87
	s_movk_i32 s26, 0x80
	s_movk_i32 s27, 0x200
.Lp1_generic:
	v_lshl_add_u32 v173, s4, 3, v171
	s_movk_i32 s5, 0x800
	v_cmp_gt_i32_e32 vcc, s5, v173
	s_and_saveexec_b64 s[20:21], vcc
	s_cbranch_execz .LBB0_100
	v_and_b32_e32 v0, 63, v170
	v_mov_b32_e32 v97, 0
	v_lshlrev_b32_e32 v2, 3, v0
	v_mov_b32_e32 v3, v97
	v_lshl_add_u64 v[2:3], s[34:35], 0, v[2:3]
	s_mov_b64 s[6:7], 0x2f00000
	v_lshl_add_u64 v[100:101], v[2:3], 0, s[6:7]
	s_mov_b64 s[6:7], 0x8f00000
	v_mbcnt_lo_u32_b32 v1, -1, 0
	v_lshl_add_u64 v[102:103], v[2:3], 0, s[6:7]
	s_mov_b64 s[6:7], 0x9f00000
	v_mbcnt_hi_u32_b32 v1, -1, v1
	v_lshl_add_u64 v[104:105], v[2:3], 0, s[6:7]
	v_and_b32_e32 v3, 64, v1
	v_add_u32_e32 v3, 64, v3
	v_xor_b32_e32 v5, 1, v1
	v_cmp_lt_i32_e32 vcc, v5, v3
	v_lshlrev_b32_e32 v96, 4, v0
	v_or_b32_e32 v2, 64, v0
	v_cndmask_b32_e32 v5, v1, v5, vcc
	v_lshlrev_b32_e32 v174, 2, v5
	v_xor_b32_e32 v5, 2, v1
	v_cmp_lt_i32_e32 vcc, v5, v3
	v_or_b32_e32 v4, 0x80, v0
	v_or_b32_e32 v6, 0xc0, v0
	v_cndmask_b32_e32 v5, v1, v5, vcc
	v_lshlrev_b32_e32 v175, 2, v5
	v_xor_b32_e32 v5, 4, v1
	v_cmp_lt_i32_e32 vcc, v5, v3
	v_lshl_add_u64 v[98:99], s[36:37], 0, v[96:97]
	v_cndmask_b32_e32 v5, v1, v5, vcc
	v_lshlrev_b32_e32 v176, 2, v5
	v_xor_b32_e32 v5, 8, v1
	v_cmp_lt_i32_e32 vcc, v5, v3
	v_lshl_add_u64 v[106:107], s[44:45], 0, v[96:97]
	v_cndmask_b32_e32 v5, v1, v5, vcc
	v_lshlrev_b32_e32 v177, 2, v5
	v_xor_b32_e32 v5, 16, v1
	v_cmp_lt_i32_e32 vcc, v5, v3
	s_mov_b64 s[22:23], 0
	s_mov_b64 s[24:25], 0x1000
	v_cndmask_b32_e32 v5, v1, v5, vcc
	v_lshlrev_b32_e32 v178, 2, v5
	v_xor_b32_e32 v5, 32, v1
	v_cmp_lt_i32_e32 vcc, v5, v3
	v_lshlrev_b32_e32 v96, 4, v0
	v_lshlrev_b32_e32 v108, 4, v2
	v_cndmask_b32_e32 v1, v1, v5, vcc
	v_lshlrev_b32_e32 v179, 2, v1
	v_lshlrev_b32_e32 v1, 2, v171
	v_lshl_add_u32 v180, s4, 5, v1
	v_mov_b32_e32 v109, v97
	v_lshlrev_b32_e32 v110, 4, v4
	v_mov_b32_e32 v111, v97
	v_lshlrev_b32_e32 v112, 4, v6
	v_mov_b32_e32 v113, v97
	v_mov_b32_e32 v181, 0x400
	v_mov_b32_e32 v182, 0x358637bd
	s_mov_b32 s40, 0xf800000
	v_mov_b32_e32 v183, 0x260
